# ctx small-GEMM K loops straight-line deep prefetch (+carry pad), staging unrolled
# speedup vs baseline: 1.0201x; 1.0109x over previous
; #define LAS __attribute__((address_space(3)))
; template <int MODE>
; __device__ __forceinline__ void ctx_small_gemm(PREF P, unsigned char* shm) {
;     ...
;             if (MODE == 0) { const int oc = col0 + r; W0 = (const bf16_t*)(wl + LO_GLU) + (size_t)((oc >> 7) * 256 + (oc & 127)) * K + q * 8; W1 = W0 + (size_t)128 * K; }
;             else if (MODE == 1) { W0 = (const bf16_t*)(wl + LO_PA + (size_t)br * SZ_P) + (size_t)(col0 + r) * K + q * 8; W1 = W0; }
;             else if (MODE == 2) { W0 = (const bf16_t*)(wl + LO_WO) + (size_t)(col0 + r) * K + q * 8; W1 = W0; }
;             else { W0 = (const bf16_t*)(wl + LO_WP) + (size_t)(col0 + r) * K + q * 8; W1 = W0; }
;             f32x4 acc0 = (f32x4){0.f, 0.f, 0.f, 0.f}, acc1 = (f32x4){0.f, 0.f, 0.f, 0.f};
; #pragma unroll 4
;             for (int ks = 0; ks < KS; ++ks) {
;                 const bf16x8 a0 = *(const LAS bf16x8*)(lds + (rt0 * 16 + r) * (K * 2) + (((ks * 4 + q) ^ r) << 4));
;                 const bf16x8 b0 = *(const bf16x8*)(W0 + ks * 32);
;                 if (MODE == 0) { const bf16x8 b1 = *(const bf16x8*)(W1 + ks * 32);
;                     acc0 = __builtin_amdgcn_mfma_f32_16x16x32_bf16(a0, b0, acc0, 0, 0, 0); acc1 = __builtin_amdgcn_mfma_f32_16x16x32_bf16(a0, b1, acc1, 0, 0, 0); }
;                 else if (MODE == 3) { acc0 = __builtin_amdgcn_mfma_f32_16x16x32_bf16(a0, b0, acc0, 0, 0, 0); }
;                 else { const bf16x8 a1 = *(const LAS bf16x8*)(lds + (rt1 * 16 + r) * (K * 2) + (((ks * 4 + q) ^ r) << 4));
;                     acc0 = __builtin_amdgcn_mfma_f32_16x16x32_bf16(a0, b0, acc0, 0, 0, 0); acc1 = __builtin_amdgcn_mfma_f32_16x16x32_bf16(a1, b0, acc1, 0, 0, 0); }
;             }
.LBB0_718:
	v_xor_b32_e32 v56, v17, v16
	v_lshl_add_u32 v57, v56, 4, v19
	v_add_u32_e32 v56, 4, v17
	v_xor_b32_e32 v56, v56, v16
	v_lshl_add_u32 v58, v56, 4, v19
	v_add_u32_e32 v56, 8, v17
	v_xor_b32_e32 v56, v56, v16
	v_lshl_add_u32 v59, v56, 4, v19
	v_add_u32_e32 v56, 12, v17
	v_xor_b32_e32 v56, v56, v16
	v_lshl_add_u32 v60, v56, 4, v19
	v_add_co_u32_e32 v62, vcc, s10, v14
	s_nop 1
	v_addc_co_u32_e32 v63, vcc, 0, v15, vcc
	v_add_co_u32_e32 v64, vcc, s11, v14
	s_nop 1
	v_addc_co_u32_e32 v65, vcc, 0, v15, vcc
	global_load_dwordx4 v[66:69], v[62:63], off
	global_load_dwordx4 v[70:73], v[64:65], off
	global_load_dwordx4 v[74:77], v[62:63], off offset:64
	global_load_dwordx4 v[78:81], v[64:65], off offset:64
	global_load_dwordx4 v[82:85], v[62:63], off offset:128
	global_load_dwordx4 v[86:89], v[64:65], off offset:128
	global_load_dwordx4 v[90:93], v[62:63], off offset:192
	global_load_dwordx4 v[94:97], v[64:65], off offset:192
	global_load_dwordx4 v[98:101], v[62:63], off offset:256
	global_load_dwordx4 v[102:105], v[64:65], off offset:256
	global_load_dwordx4 v[106:109], v[62:63], off offset:320
	global_load_dwordx4 v[110:113], v[64:65], off offset:320
	global_load_dwordx4 v[114:117], v[62:63], off offset:384
	global_load_dwordx4 v[118:121], v[64:65], off offset:384
	global_load_dwordx4 v[122:125], v[62:63], off offset:448
	global_load_dwordx4 v[126:129], v[64:65], off offset:448
	global_load_dwordx4 v[130:133], v[62:63], off offset:512
	global_load_dwordx4 v[134:137], v[64:65], off offset:512
	global_load_dwordx4 v[138:141], v[62:63], off offset:576
	global_load_dwordx4 v[142:145], v[64:65], off offset:576
	global_load_dwordx4 v[146:149], v[62:63], off offset:640
	global_load_dwordx4 v[150:153], v[64:65], off offset:640
	global_load_dwordx4 v[154:157], v[62:63], off offset:704
	global_load_dwordx4 v[158:161], v[64:65], off offset:704
	global_load_dwordx4 v[162:165], v[62:63], off offset:768
	global_load_dwordx4 v[166:169], v[64:65], off offset:768
	global_load_dwordx4 v[170:173], v[62:63], off offset:832
	global_load_dwordx4 v[174:177], v[64:65], off offset:832
	global_load_dwordx4 v[178:181], v[62:63], off offset:896
	global_load_dwordx4 v[182:185], v[64:65], off offset:896
	global_load_dwordx4 v[186:189], v[62:63], off offset:960
	global_load_dwordx4 v[190:193], v[64:65], off offset:960
	ds_read_b128 v[194:197], v57
	ds_read_b128 v[198:201], v58
	ds_read_b128 v[202:205], v59
	ds_read_b128 v[206:209], v60
	ds_read_b128 v[210:213], v57 offset:256
	ds_read_b128 v[214:217], v58 offset:256
	ds_read_b128 v[218:221], v59 offset:256
	ds_read_b128 v[222:225], v60 offset:256
	s_waitcnt vmcnt(30) lgkmcnt(7)
	v_mfma_f32_16x16x32_bf16 v[2:5], v[194:197], v[66:69], v[2:5]
	v_mfma_f32_16x16x32_bf16 v[6:9], v[194:197], v[70:73], v[6:9]
	global_load_dwordx4 v[66:69], v[62:63], off offset:1024
	global_load_dwordx4 v[70:73], v[64:65], off offset:1024
	ds_read_b128 v[194:197], v57 offset:512
	s_waitcnt vmcnt(30) lgkmcnt(7)
	v_mfma_f32_16x16x32_bf16 v[2:5], v[198:201], v[74:77], v[2:5]
	v_mfma_f32_16x16x32_bf16 v[6:9], v[198:201], v[78:81], v[6:9]
	global_load_dwordx4 v[74:77], v[62:63], off offset:1088
	global_load_dwordx4 v[78:81], v[64:65], off offset:1088
	ds_read_b128 v[198:201], v58 offset:512
	s_waitcnt vmcnt(30) lgkmcnt(7)
	v_mfma_f32_16x16x32_bf16 v[2:5], v[202:205], v[82:85], v[2:5]
	v_mfma_f32_16x16x32_bf16 v[6:9], v[202:205], v[86:89], v[6:9]
	global_load_dwordx4 v[82:85], v[62:63], off offset:1152
	global_load_dwordx4 v[86:89], v[64:65], off offset:1152
	ds_read_b128 v[202:205], v59 offset:512
	s_waitcnt vmcnt(30) lgkmcnt(7)
	v_mfma_f32_16x16x32_bf16 v[2:5], v[206:209], v[90:93], v[2:5]
	v_mfma_f32_16x16x32_bf16 v[6:9], v[206:209], v[94:97], v[6:9]
	global_load_dwordx4 v[90:93], v[62:63], off offset:1216
	global_load_dwordx4 v[94:97], v[64:65], off offset:1216
	ds_read_b128 v[206:209], v60 offset:512
	s_waitcnt vmcnt(30) lgkmcnt(7)
	v_mfma_f32_16x16x32_bf16 v[2:5], v[210:213], v[98:101], v[2:5]
	v_mfma_f32_16x16x32_bf16 v[6:9], v[210:213], v[102:105], v[6:9]
	global_load_dwordx4 v[98:101], v[62:63], off offset:1280
	global_load_dwordx4 v[102:105], v[64:65], off offset:1280
	ds_read_b128 v[210:213], v57 offset:768
	s_waitcnt vmcnt(30) lgkmcnt(7)
	v_mfma_f32_16x16x32_bf16 v[2:5], v[214:217], v[106:109], v[2:5]
	v_mfma_f32_16x16x32_bf16 v[6:9], v[214:217], v[110:113], v[6:9]
	global_load_dwordx4 v[106:109], v[62:63], off offset:1344
	global_load_dwordx4 v[110:113], v[64:65], off offset:1344
	ds_read_b128 v[214:217], v58 offset:768
	s_waitcnt vmcnt(30) lgkmcnt(7)
	v_mfma_f32_16x16x32_bf16 v[2:5], v[218:221], v[114:117], v[2:5]
	v_mfma_f32_16x16x32_bf16 v[6:9], v[218:221], v[118:121], v[6:9]
	global_load_dwordx4 v[114:117], v[62:63], off offset:1408
	global_load_dwordx4 v[118:121], v[64:65], off offset:1408
	ds_read_b128 v[218:221], v59 offset:768
	s_waitcnt vmcnt(30) lgkmcnt(7)
	v_mfma_f32_16x16x32_bf16 v[2:5], v[222:225], v[122:125], v[2:5]
	v_mfma_f32_16x16x32_bf16 v[6:9], v[222:225], v[126:129], v[6:9]
	global_load_dwordx4 v[122:125], v[62:63], off offset:1472
	global_load_dwordx4 v[126:129], v[64:65], off offset:1472
	ds_read_b128 v[222:225], v60 offset:768
	s_waitcnt vmcnt(30) lgkmcnt(7)
	v_mfma_f32_16x16x32_bf16 v[2:5], v[194:197], v[130:133], v[2:5]
	v_mfma_f32_16x16x32_bf16 v[6:9], v[194:197], v[134:137], v[6:9]
	global_load_dwordx4 v[130:133], v[62:63], off offset:1536
	global_load_dwordx4 v[134:137], v[64:65], off offset:1536
	ds_read_b128 v[194:197], v57 offset:1024
	s_waitcnt vmcnt(30) lgkmcnt(7)
; #define LAS __attribute__((address_space(3)))
; template <int MODE>
; __device__ __forceinline__ void ctx_small_gemm(PREF P, unsigned char* shm) {
;     ...
; #pragma unroll 4
;             for (int ks = 0; ks < KS; ++ks) {
;                 const bf16x8 a0 = *(const LAS bf16x8*)(lds + (rt0 * 16 + r) * (K * 2) + (((ks * 4 + q) ^ r) << 4));
;                 const bf16x8 b0 = *(const bf16x8*)(W0 + ks * 32);
;                 if (MODE == 0) { const bf16x8 b1 = *(const bf16x8*)(W1 + ks * 32);
;                     acc0 = __builtin_amdgcn_mfma_f32_16x16x32_bf16(a0, b0, acc0, 0, 0, 0); acc1 = __builtin_amdgcn_mfma_f32_16x16x32_bf16(a0, b1, acc1, 0, 0, 0); }
;                 else if (MODE == 3) { acc0 = __builtin_amdgcn_mfma_f32_16x16x32_bf16(a0, b0, acc0, 0, 0, 0); }
;                 else { const bf16x8 a1 = *(const LAS bf16x8*)(lds + (rt1 * 16 + r) * (K * 2) + (((ks * 4 + q) ^ r) << 4));
;                     acc0 = __builtin_amdgcn_mfma_f32_16x16x32_bf16(a0, b0, acc0, 0, 0, 0); acc1 = __builtin_amdgcn_mfma_f32_16x16x32_bf16(a1, b0, acc1, 0, 0, 0); }
;             }
	v_mfma_f32_16x16x32_bf16 v[2:5], v[198:201], v[138:141], v[2:5]
	v_mfma_f32_16x16x32_bf16 v[6:9], v[198:201], v[142:145], v[6:9]
	global_load_dwordx4 v[138:141], v[62:63], off offset:1600
	global_load_dwordx4 v[142:145], v[64:65], off offset:1600
	ds_read_b128 v[198:201], v58 offset:1024
	s_waitcnt vmcnt(30) lgkmcnt(7)
	v_mfma_f32_16x16x32_bf16 v[2:5], v[202:205], v[146:149], v[2:5]
	v_mfma_f32_16x16x32_bf16 v[6:9], v[202:205], v[150:153], v[6:9]
	global_load_dwordx4 v[146:149], v[62:63], off offset:1664
	global_load_dwordx4 v[150:153], v[64:65], off offset:1664
	ds_read_b128 v[202:205], v59 offset:1024
	s_waitcnt vmcnt(30) lgkmcnt(7)
	v_mfma_f32_16x16x32_bf16 v[2:5], v[206:209], v[154:157], v[2:5]
	v_mfma_f32_16x16x32_bf16 v[6:9], v[206:209], v[158:161], v[6:9]
	global_load_dwordx4 v[154:157], v[62:63], off offset:1728
	global_load_dwordx4 v[158:161], v[64:65], off offset:1728
	ds_read_b128 v[206:209], v60 offset:1024
	s_waitcnt vmcnt(30) lgkmcnt(7)
	v_mfma_f32_16x16x32_bf16 v[2:5], v[210:213], v[162:165], v[2:5]
	v_mfma_f32_16x16x32_bf16 v[6:9], v[210:213], v[166:169], v[6:9]
	global_load_dwordx4 v[162:165], v[62:63], off offset:1792
	global_load_dwordx4 v[166:169], v[64:65], off offset:1792
	ds_read_b128 v[210:213], v57 offset:1280
	s_waitcnt vmcnt(30) lgkmcnt(7)
	v_mfma_f32_16x16x32_bf16 v[2:5], v[214:217], v[170:173], v[2:5]
	v_mfma_f32_16x16x32_bf16 v[6:9], v[214:217], v[174:177], v[6:9]
	global_load_dwordx4 v[170:173], v[62:63], off offset:1856
	global_load_dwordx4 v[174:177], v[64:65], off offset:1856
	ds_read_b128 v[214:217], v58 offset:1280
	s_waitcnt vmcnt(30) lgkmcnt(7)
	v_mfma_f32_16x16x32_bf16 v[2:5], v[218:221], v[178:181], v[2:5]
	v_mfma_f32_16x16x32_bf16 v[6:9], v[218:221], v[182:185], v[6:9]
	global_load_dwordx4 v[178:181], v[62:63], off offset:1920
	global_load_dwordx4 v[182:185], v[64:65], off offset:1920
	ds_read_b128 v[218:221], v59 offset:1280
	s_waitcnt vmcnt(30) lgkmcnt(7)
	v_mfma_f32_16x16x32_bf16 v[2:5], v[222:225], v[186:189], v[2:5]
	v_mfma_f32_16x16x32_bf16 v[6:9], v[222:225], v[190:193], v[6:9]
	global_load_dwordx4 v[186:189], v[62:63], off offset:1984
	global_load_dwordx4 v[190:193], v[64:65], off offset:1984
	ds_read_b128 v[222:225], v60 offset:1280
	s_waitcnt vmcnt(30) lgkmcnt(7)
	v_mfma_f32_16x16x32_bf16 v[2:5], v[194:197], v[66:69], v[2:5]
	v_mfma_f32_16x16x32_bf16 v[6:9], v[194:197], v[70:73], v[6:9]
	ds_read_b128 v[194:197], v57 offset:1536
	s_waitcnt vmcnt(28) lgkmcnt(7)
	v_mfma_f32_16x16x32_bf16 v[2:5], v[198:201], v[74:77], v[2:5]
	v_mfma_f32_16x16x32_bf16 v[6:9], v[198:201], v[78:81], v[6:9]
	ds_read_b128 v[198:201], v58 offset:1536
	s_waitcnt vmcnt(26) lgkmcnt(7)
	v_mfma_f32_16x16x32_bf16 v[2:5], v[202:205], v[82:85], v[2:5]
	v_mfma_f32_16x16x32_bf16 v[6:9], v[202:205], v[86:89], v[6:9]
	ds_read_b128 v[202:205], v59 offset:1536
	s_waitcnt vmcnt(24) lgkmcnt(7)
	v_mfma_f32_16x16x32_bf16 v[2:5], v[206:209], v[90:93], v[2:5]
	v_mfma_f32_16x16x32_bf16 v[6:9], v[206:209], v[94:97], v[6:9]
	ds_read_b128 v[206:209], v60 offset:1536
	s_waitcnt vmcnt(22) lgkmcnt(7)
	v_mfma_f32_16x16x32_bf16 v[2:5], v[210:213], v[98:101], v[2:5]
	v_mfma_f32_16x16x32_bf16 v[6:9], v[210:213], v[102:105], v[6:9]
	ds_read_b128 v[210:213], v57 offset:1792
	s_waitcnt vmcnt(20) lgkmcnt(7)
	v_mfma_f32_16x16x32_bf16 v[2:5], v[214:217], v[106:109], v[2:5]
	v_mfma_f32_16x16x32_bf16 v[6:9], v[214:217], v[110:113], v[6:9]
	ds_read_b128 v[214:217], v58 offset:1792
	s_waitcnt vmcnt(18) lgkmcnt(7)
	v_mfma_f32_16x16x32_bf16 v[2:5], v[218:221], v[114:117], v[2:5]
	v_mfma_f32_16x16x32_bf16 v[6:9], v[218:221], v[118:121], v[6:9]
	ds_read_b128 v[218:221], v59 offset:1792
	s_waitcnt vmcnt(16) lgkmcnt(7)
	v_mfma_f32_16x16x32_bf16 v[2:5], v[222:225], v[122:125], v[2:5]
	v_mfma_f32_16x16x32_bf16 v[6:9], v[222:225], v[126:129], v[6:9]
	ds_read_b128 v[222:225], v60 offset:1792
	s_waitcnt vmcnt(14) lgkmcnt(7)
	v_mfma_f32_16x16x32_bf16 v[2:5], v[194:197], v[130:133], v[2:5]
	v_mfma_f32_16x16x32_bf16 v[6:9], v[194:197], v[134:137], v[6:9]
	s_waitcnt vmcnt(12) lgkmcnt(6)
; #define LAS __attribute__((address_space(3)))
; __device__ __forceinline__ float bf2f(unsigned v) { return __uint_as_float(v << 16); }
; __device__ __forceinline__ unsigned cvt_pk_bf16(float lo, float hi) { unsigned r; asm volatile("v_cvt_pk_bf16_f32 %0, %1, %2" : "=v"(r) : "v"(lo), "v"(hi)); return r; }
; __device__ __forceinline__ float sigmoidf_(float x) { return __builtin_amdgcn_rcpf(1.0f + __expf(-x)); }
; __device__ __forceinline__ float siluf_(float x) { return x * __builtin_amdgcn_rcpf(1.0f + __expf(-x)); }
; template <int MODE>
; __device__ __forceinline__ void ctx_small_gemm(PREF P, unsigned char* shm) {
;     ...
; #pragma unroll 4
;             for (int ks = 0; ks < KS; ++ks) {
;                 const bf16x8 a0 = *(const LAS bf16x8*)(lds + (rt0 * 16 + r) * (K * 2) + (((ks * 4 + q) ^ r) << 4));
;                 const bf16x8 b0 = *(const bf16x8*)(W0 + ks * 32);
;                 if (MODE == 0) { const bf16x8 b1 = *(const bf16x8*)(W1 + ks * 32);
;                     acc0 = __builtin_amdgcn_mfma_f32_16x16x32_bf16(a0, b0, acc0, 0, 0, 0); acc1 = __builtin_amdgcn_mfma_f32_16x16x32_bf16(a0, b1, acc1, 0, 0, 0); }
;                 else if (MODE == 3) { acc0 = __builtin_amdgcn_mfma_f32_16x16x32_bf16(a0, b0, acc0, 0, 0, 0); }
;                 else { const bf16x8 a1 = *(const LAS bf16x8*)(lds + (rt1 * 16 + r) * (K * 2) + (((ks * 4 + q) ^ r) << 4));
;                     acc0 = __builtin_amdgcn_mfma_f32_16x16x32_bf16(a0, b0, acc0, 0, 0, 0); acc1 = __builtin_amdgcn_mfma_f32_16x16x32_bf16(a1, b0, acc1, 0, 0, 0); }
;             }
;             const int col = col0 + r;
;             if (MODE == 0) { bf16_t* BBo = (bf16_t*)(P.ws + O_BB); float zq[4];
; #pragma unroll
;                 for (int i = 0; i < 4; ++i) { const int row = row_base + rt0 * 16 + q * 4 + i; zq[i] = bf2f(parts[E_PZB + (size_t)row * 1024 + col]); }
; #pragma unroll
;                 for (int i = 0; i < 4; ++i) { const int row = row_base + rt0 * 16 + q * 4 + i; const float z = zq[i];
;                     BBo[(size_t)row * 1024 + col] = (bf16_t)(cvt_pk_bf16(acc0[i] * sigmoidf_(acc1[i]) * siluf_(z), 0.f) & 0xffffu); }
	v_mfma_f32_16x16x32_bf16 v[2:5], v[198:201], v[138:141], v[2:5]
	v_mfma_f32_16x16x32_bf16 v[6:9], v[198:201], v[142:145], v[6:9]
	s_waitcnt vmcnt(10) lgkmcnt(5)
	v_mfma_f32_16x16x32_bf16 v[2:5], v[202:205], v[146:149], v[2:5]
	v_mfma_f32_16x16x32_bf16 v[6:9], v[202:205], v[150:153], v[6:9]
	s_waitcnt vmcnt(8) lgkmcnt(4)
	v_mfma_f32_16x16x32_bf16 v[2:5], v[206:209], v[154:157], v[2:5]
	v_mfma_f32_16x16x32_bf16 v[6:9], v[206:209], v[158:161], v[6:9]
	s_waitcnt vmcnt(6) lgkmcnt(3)
	v_mfma_f32_16x16x32_bf16 v[2:5], v[210:213], v[162:165], v[2:5]
	v_mfma_f32_16x16x32_bf16 v[6:9], v[210:213], v[166:169], v[6:9]
	s_waitcnt vmcnt(4) lgkmcnt(2)
	v_mfma_f32_16x16x32_bf16 v[2:5], v[214:217], v[170:173], v[2:5]
	v_mfma_f32_16x16x32_bf16 v[6:9], v[214:217], v[174:177], v[6:9]
	s_waitcnt vmcnt(2) lgkmcnt(1)
	v_mfma_f32_16x16x32_bf16 v[2:5], v[218:221], v[178:181], v[2:5]
	v_mfma_f32_16x16x32_bf16 v[6:9], v[218:221], v[182:185], v[6:9]
	s_waitcnt vmcnt(0) lgkmcnt(0)
	v_mfma_f32_16x16x32_bf16 v[2:5], v[222:225], v[186:189], v[2:5]
	v_mfma_f32_16x16x32_bf16 v[6:9], v[222:225], v[190:193], v[6:9]
	s_mov_b64 s[16:17], 0x800
	v_add_u32_e32 v10, 0x80, v10
	s_cmpk_eq_i32 s16, 0x800
	s_lshl_b32 s16, s0, 5
	s_and_b32 s16, s16, 0x3e0
	v_add_u32_e32 v14, s20, v20
	v_or_b32_e32 v10, s16, v18
	v_ashrrev_i32_e32 v15, 31, v14
	v_lshlrev_b32_e32 v10, 1, v10
	v_lshlrev_b64 v[26:27], 11, v[14:15]
	v_or_b32_e32 v30, 1, v14
	v_or_b32_e32 v34, 2, v14
	v_or_b32_e32 v14, 3, v14
	v_lshl_add_u64 v[24:25], s[14:15], 0, v[10:11]
	v_ashrrev_i32_e32 v31, 31, v30
	v_ashrrev_i32_e32 v35, 31, v34
	v_ashrrev_i32_e32 v15, 31, v14
	v_lshl_add_u64 v[28:29], v[24:25], 0, v[26:27]
	v_lshlrev_b64 v[30:31], 11, v[30:31]
	v_lshlrev_b64 v[34:35], 11, v[34:35]
	v_lshlrev_b64 v[14:15], 11, v[14:15]
	v_lshl_add_u64 v[32:33], v[24:25], 0, v[30:31]
	v_lshl_add_u64 v[36:37], v[24:25], 0, v[34:35]
	v_lshl_add_u64 v[24:25], v[24:25], 0, v[14:15]
	global_load_ushort v23, v[28:29], off
	global_load_ushort v38, v[32:33], off
	global_load_ushort v39, v[36:37], off
	global_load_ushort v40, v[24:25], off
	v_mul_f32_e32 v6, 0xbfb8aa3b, v6
	v_mul_f32_e32 v8, 0xbfb8aa3b, v8
	v_mul_f32_e32 v9, 0xbfb8aa3b, v9
	v_exp_f32_e32 v24, v6
	v_mul_f32_e32 v7, 0xbfb8aa3b, v7
	v_exp_f32_e32 v28, v8
	v_exp_f32_e32 v29, v9
	v_exp_f32_e32 v25, v7
	v_lshl_add_u64 v[6:7], s[12:13], 0, v[10:11]
	v_add_f32_e32 v10, 1.0, v24
	v_add_f32_e32 v28, 1.0, v28
	v_add_f32_e32 v29, 1.0, v29
	v_rcp_f32_e32 v10, v10
	v_lshl_add_u64 v[8:9], v[6:7], 0, v[26:27]
	v_add_f32_e32 v32, 1.0, v25
	v_lshl_add_u64 v[24:25], v[6:7], 0, v[30:31]
	v_lshl_add_u64 v[26:27], v[6:7], 0, v[34:35]
	v_lshl_add_u64 v[6:7], v[6:7], 0, v[14:15]
	v_rcp_f32_e32 v15, v28
	v_rcp_f32_e32 v28, v29
	v_rcp_f32_e32 v14, v32
	v_mul_f32_e32 v2, v2, v10
	v_mul_f32_e32 v4, v4, v15
	v_mul_f32_e32 v5, v5, v28
	v_mul_f32_e32 v3, v3, v14
	s_add_i32 s0, s0, s33
	s_add_i32 s1, s1, s2
	s_cmpk_gt_i32 s0, 0xff
	s_waitcnt vmcnt(3)
	v_lshlrev_b32_e32 v10, 16, v23
	v_mul_f32_e32 v28, 0xbfb8aa3b, v10
	s_waitcnt vmcnt(2)
	v_lshlrev_b32_e32 v14, 16, v38
	v_exp_f32_e32 v28, v28
	s_waitcnt vmcnt(1)
	v_lshlrev_b32_e32 v15, 16, v39
	v_mul_f32_e32 v29, 0xbfb8aa3b, v14
	s_waitcnt vmcnt(0)
	v_lshlrev_b32_e32 v23, 16, v40
	v_mul_f32_e32 v30, 0xbfb8aa3b, v15
	v_exp_f32_e32 v29, v29
	v_mul_f32_e32 v31, 0xbfb8aa3b, v23
	v_exp_f32_e32 v30, v30
	v_exp_f32_e32 v31, v31
	v_add_f32_e32 v28, 1.0, v28
	v_rcp_f32_e32 v28, v28
	v_add_f32_e32 v29, 1.0, v29
	v_add_f32_e32 v30, 1.0, v30
	v_rcp_f32_e32 v29, v29
	v_add_f32_e32 v31, 1.0, v31
	v_rcp_f32_e32 v30, v30
	v_rcp_f32_e32 v31, v31
	v_mul_f32_e32 v10, v28, v10
	v_mul_f32_e32 v2, v2, v10
	v_mul_f32_e32 v14, v29, v14
	v_cvt_pk_bf16_f32 v2, v2, v11
	v_mul_f32_e32 v15, v30, v15
	v_mul_f32_e32 v3, v3, v14
	global_store_short v[8:9], v2, off
	v_cvt_pk_bf16_f32 v2, v3, v11
	v_mul_f32_e32 v23, v31, v23
	v_mul_f32_e32 v4, v4, v15
	global_store_short v[24:25], v2, off
	v_cvt_pk_bf16_f32 v2, v4, v11
	v_mul_f32_e32 v5, v5, v23
	global_store_short v[26:27], v2, off
	v_cvt_pk_bf16_f32 v2, v5, v11
	global_store_short v[6:7], v2, off
	s_barrier
	s_cbranch_scc0 .LBB0_714
